# NSA gate values 2 and 3 fetched with gate 1 (two fewer exposed round trips per NSA unit), final stack
# speedup vs baseline: 1.0143x; 1.0002x over previous
; __global__ void __launch_bounds__(NTHR, 2) hybrid_fwd(P p) {
;     ...
;             for (;;) {
;                 if (tid == 0) *qslot = atomicAdd(qctr, 1u);
;                 __syncthreads();
;                 const int v = (int)*qslot;
;                 __syncthreads();
.LBB0_518:
	s_setprio 0
	v_mov_b64_e32 v[192:193], 0x200
	s_mov_b64 s[2:3], 0

; #define LAS __attribute__((address_space(3)))
; DI unsigned pk2(float lo, float hi) { f32x2_t v = {lo, hi}; bf16x2_t b = __builtin_convertvector(v, bf16x2_t); return __builtin_bit_cast(unsigned, b); }
; #define NSA_GATE(k) sigmoidf_(((const float*)(p.ws + WS_SCAL))[(size_t)(b * T + t) * 32 + 8 + hn * 3 + (k)])
; template <int STEP> DI void nsa_store(const f32x16 (&o)[4], float sc, ldsp acc, bf16* orow) {
; #pragma unroll
;     for (int db = 0; db < 4; ++db)
; #pragma unroll
;         for (int g4 = 0; g4 < 4; ++g4) {
;             f32x4 v; v[0] = o[db][4 * g4] * sc; v[1] = o[db][4 * g4 + 1] * sc; v[2] = o[db][4 * g4 + 2] * sc; v[3] = o[db][4 * g4 + 3] * sc;
;             ldsp a = acc + (db * 4 + g4) * 512;
;             if (STEP >= 1) { const u32x2 r = *(const LAS u32x2*)a;
;                 v[0] += __builtin_bit_cast(float, r.x << 16); v[1] += __builtin_bit_cast(float, r.x & 0xffff0000u); v[2] += __builtin_bit_cast(float, r.y << 16); v[3] += __builtin_bit_cast(float, r.y & 0xffff0000u); }
;             u32x2 wv; wv.x = pk2(v[0], v[1]); wv.y = pk2(v[2], v[3]);
;             if (STEP <= 1) *(LAS u32x2*)a = wv; else *(u32x2*)(orow + 32 * db + 8 * g4) = wv;
;         }
; DI void nsa_unit(const P& p, ldsp lds, int u, int l, int wv) {
;     ...
;     nsa_store<0>(o, NSA_GATE(0), NSA_OACC, NSA_OROW);
;     zero_o(o); c.m = NINF; c.l = 0.f; c.tile0 = 0; c.whi = 1 << 30;
;     c.kmat = heads + ((size_t)(28 + g) * M + b * T) * HD; c.vtm = VT + ((size_t)(8 + g) * (M / 64) + b * (T / 64)) * 8192; c.vpitch = 64;
;     attn_run<MD_SEL>(c, q, o, lds, tid, wv);
.LBB0_881:
	s_or_b64 exec, exec, s[2:3]
	v_readlane_b32 s1, v255, 20
	v_mad_u32_u24 v0, v196, 3, 8
	v_readlane_b32 s2, v253, 62
	v_add_u32_e32 v156, s1, v148
	v_ashrrev_i32_e32 v157, 31, v156
	v_lshlrev_b64 v[66:67], 5, v[156:157]
	v_lshl_add_u64 v[158:159], v[66:67], 0, v[0:1]
	v_readlane_b32 s3, v253, 63
	s_waitcnt lgkmcnt(0)
	s_barrier
	v_lshl_add_u64 v[66:67], v[158:159], 2, s[2:3]
	global_load_dword v0, v[66:67], off
	global_load_dword v192, v[66:67], off offset:4
	global_load_dword v193, v[66:67], off offset:8
	v_lshl_add_u32 v67, v166, 13, s19
	v_lshlrev_b32_e32 v68, 3, v167
	v_add_u32_e32 v209, v67, v68
	v_readlane_b32 s1, v254, 33
	v_readlane_b32 s6, v253, 10
	v_readlane_b32 s7, v253, 11
	v_mov_b32_e32 v66, s1
	v_readlane_b32 s1, v255, 21
	ds_read_b32 v66, v66
	s_brev_b32 s1, s1
	s_lshr_b32 s4, s1, 9
	s_add_u32 s1, s6, s4
	s_addc_u32 s19, s7, 0
	s_waitcnt lgkmcnt(0)
	v_readfirstlane_b32 s30, v66
	s_waitcnt vmcnt(0)
	v_mul_f32_e32 v0, 0xbfb8aa3b, v0
	v_exp_f32_e32 v0, v0
	s_nop 0
	v_add_f32_e32 v0, 1.0, v0
	v_div_scale_f32 v67, s[2:3], v0, v0, 1.0
	v_rcp_f32_e32 v68, v67
	v_div_scale_f32 v69, vcc, 1.0, v0, 1.0
	v_readlane_b32 s2, v254, 2
	v_fma_f32 v70, -v67, v68, 1.0
	v_fmac_f32_e32 v68, v70, v68
	v_mul_f32_e32 v70, v69, v68
	v_fma_f32 v71, -v67, v70, v69
	v_fmac_f32_e32 v70, v71, v68
	v_fma_f32 v67, -v67, v70, v69
	v_div_fmas_f32 v67, v67, v68, v70
	v_div_fixup_f32 v0, v67, v0, 1.0
	v_pk_mul_f32 v[50:51], v[50:51], v[0:1] op_sel_hi:[1,0]
	v_pk_mul_f32 v[52:53], v[52:53], v[0:1] op_sel_hi:[1,0]
	v_pk_mul_f32 v[54:55], v[54:55], v[0:1] op_sel_hi:[1,0]
	v_pk_mul_f32 v[56:57], v[56:57], v[0:1] op_sel_hi:[1,0]
	v_pk_mul_f32 v[2:3], v[2:3], v[0:1] op_sel_hi:[1,0]
	v_pk_mul_f32 v[4:5], v[4:5], v[0:1] op_sel_hi:[1,0]
	v_pk_mul_f32 v[6:7], v[6:7], v[0:1] op_sel_hi:[1,0]
	v_pk_mul_f32 v[8:9], v[8:9], v[0:1] op_sel_hi:[1,0]
	v_pk_mul_f32 v[10:11], v[10:11], v[0:1] op_sel_hi:[1,0]
	v_pk_mul_f32 v[12:13], v[12:13], v[0:1] op_sel_hi:[1,0]
	v_pk_mul_f32 v[14:15], v[14:15], v[0:1] op_sel_hi:[1,0]
	v_pk_mul_f32 v[16:17], v[16:17], v[0:1] op_sel_hi:[1,0]
	s_add_u32 s26, s2, s4
	v_readlane_b32 s2, v254, 3
	v_cmp_gt_i32_e32 vcc, 1, v66
	v_pk_mul_f32 v[58:59], v[58:59], v[0:1] op_sel_hi:[1,0]
	v_pk_mul_f32 v[60:61], v[60:61], v[0:1] op_sel_hi:[1,0]
	v_pk_mul_f32 v[62:63], v[62:63], v[0:1] op_sel_hi:[1,0]
	v_pk_mul_f32 v[64:65], v[64:65], v[0:1] op_sel_hi:[1,0]
	v_pk_mul_f32 v[34:35], v[34:35], v[0:1] op_sel_hi:[1,0]
	v_pk_mul_f32 v[36:37], v[36:37], v[0:1] op_sel_hi:[1,0]
	v_pk_mul_f32 v[38:39], v[38:39], v[0:1] op_sel_hi:[1,0]
	v_pk_mul_f32 v[40:41], v[40:41], v[0:1] op_sel_hi:[1,0]
	v_pk_mul_f32 v[42:43], v[42:43], v[0:1] op_sel_hi:[1,0]
	v_pk_mul_f32 v[44:45], v[44:45], v[0:1] op_sel_hi:[1,0]
	v_pk_mul_f32 v[46:47], v[46:47], v[0:1] op_sel_hi:[1,0]
	v_pk_mul_f32 v[48:49], v[48:49], v[0:1] op_sel_hi:[1,0]
	v_pk_mul_f32 v[18:19], v[18:19], v[0:1] op_sel_hi:[1,0]
	v_pk_mul_f32 v[20:21], v[20:21], v[0:1] op_sel_hi:[1,0]
	v_pk_mul_f32 v[22:23], v[22:23], v[0:1] op_sel_hi:[1,0]
	v_pk_mul_f32 v[24:25], v[24:25], v[0:1] op_sel_hi:[1,0]
	v_pk_mul_f32 v[26:27], v[26:27], v[0:1] op_sel_hi:[1,0]
	v_pk_mul_f32 v[28:29], v[28:29], v[0:1] op_sel_hi:[1,0]
	v_pk_mul_f32 v[30:31], v[30:31], v[0:1] op_sel_hi:[1,0]
	v_pk_mul_f32 v[32:33], v[32:33], v[0:1] op_sel_hi:[1,0]
	v_cvt_pk_bf16_f32 v50, v50, v51
	v_cvt_pk_bf16_f32 v51, v52, v53
	v_cvt_pk_bf16_f32 v52, v54, v55
	v_cvt_pk_bf16_f32 v53, v56, v57
	v_cvt_pk_bf16_f32 v2, v2, v3
	v_cvt_pk_bf16_f32 v3, v4, v5
	v_cvt_pk_bf16_f32 v4, v6, v7
	v_cvt_pk_bf16_f32 v5, v8, v9
	v_cvt_pk_bf16_f32 v6, v10, v11
	v_cvt_pk_bf16_f32 v7, v12, v13
	v_cvt_pk_bf16_f32 v8, v14, v15
	v_cvt_pk_bf16_f32 v9, v16, v17
	s_addc_u32 s27, s2, 0
	s_and_b64 vcc, exec, vcc
	v_cvt_pk_bf16_f32 v54, v58, v59
	v_cvt_pk_bf16_f32 v55, v60, v61
	v_cvt_pk_bf16_f32 v56, v62, v63
	v_cvt_pk_bf16_f32 v57, v64, v65
	v_cvt_pk_bf16_f32 v34, v34, v35
	v_cvt_pk_bf16_f32 v35, v36, v37
	v_cvt_pk_bf16_f32 v36, v38, v39
	v_cvt_pk_bf16_f32 v37, v40, v41
	v_cvt_pk_bf16_f32 v38, v42, v43
	v_cvt_pk_bf16_f32 v39, v44, v45
	v_cvt_pk_bf16_f32 v40, v46, v47
	v_cvt_pk_bf16_f32 v41, v48, v49
	v_cvt_pk_bf16_f32 v18, v18, v19
	v_cvt_pk_bf16_f32 v19, v20, v21
	v_cvt_pk_bf16_f32 v20, v22, v23
	v_cvt_pk_bf16_f32 v21, v24, v25
	v_cvt_pk_bf16_f32 v22, v26, v27
	v_cvt_pk_bf16_f32 v23, v28, v29
	v_cvt_pk_bf16_f32 v24, v30, v31
	v_cvt_pk_bf16_f32 v25, v32, v33
	ds_write2st64_b64 v209, v[50:51], v[52:53] offset1:1
	ds_write2st64_b64 v209, v[54:55], v[56:57] offset0:2 offset1:3
	ds_write2st64_b64 v209, v[34:35], v[36:37] offset0:4 offset1:5
	ds_write2st64_b64 v209, v[38:39], v[40:41] offset0:6 offset1:7
	ds_write2st64_b64 v209, v[18:19], v[20:21] offset0:8 offset1:9
	ds_write2st64_b64 v209, v[22:23], v[24:25] offset0:10 offset1:11
	ds_write2st64_b64 v209, v[2:3], v[4:5] offset0:12 offset1:13
	ds_write2st64_b64 v209, v[6:7], v[8:9] offset0:14 offset1:15
	s_cbranch_vccnz .LBB0_928
	v_readlane_b32 s2, v254, 32
	s_add_u32 s12, s1, 0x7000000
	s_addc_u32 s13, s19, 0
	v_mov_b32_e32 v0, s2
	ds_read_b32 v2, v0
	s_add_u32 s14, s26, 0x2000000
	s_addc_u32 s15, s27, 0
	s_cmp_lg_u32 s30, 1
	s_cselect_b64 s[4:5], -1, 0
	s_waitcnt lgkmcnt(0)
	v_ashrrev_i32_e32 v3, 31, v2
	v_lshlrev_b64 v[2:3], 14, v[2:3]
	v_lshl_add_u64 v[4:5], s[12:13], 0, v[2:3]
	v_lshl_add_u64 v[2:3], s[14:15], 0, v[2:3]
	v_lshl_add_u64 v[6:7], v[4:5], 0, v[150:151]
	v_lshl_add_u64 v[4:5], v[4:5], 0, v[152:153]
	global_load_dwordx4 v[130:133], v[6:7], off
	global_load_dwordx4 v[134:137], v[4:5], off
	v_lshl_add_u64 v[4:5], v[2:3], 0, v[150:151]
	v_lshl_add_u64 v[2:3], v[2:3], 0, v[152:153]
	global_load_dwordx4 v[138:141], v[4:5], off
	global_load_dwordx4 v[142:145], v[2:3], off
	s_cmp_eq_u32 s30, 1
	v_readlane_b32 s6, v255, 22
	s_cselect_b64 s[2:3], -1, 0
	v_readlane_b32 s7, v255, 23
	s_or_b64 s[2:3], s[6:7], s[2:3]
	v_mov_b32_e32 v190, 0
	s_and_b64 vcc, exec, s[2:3]
	s_waitcnt vmcnt(3)
	ds_write_b128 v202, v[130:133]
	s_waitcnt vmcnt(2)
	ds_write_b128 v202, v[134:137] offset:8704
	s_waitcnt vmcnt(1)
	ds_write2_b64 v207, v[138:139], v[140:141] offset1:2
	s_waitcnt vmcnt(0)
	ds_write2_b64 v208, v[142:143], v[144:145] offset0:128 offset1:130
	s_waitcnt lgkmcnt(0)
	s_barrier
	ds_read_b32 v0, v0
	s_waitcnt lgkmcnt(0)
	v_readfirstlane_b32 s20, v0
	s_cbranch_vccnz .LBB0_884
	v_readlane_b32 s2, v254, 34
	s_nop 1
	v_mov_b32_e32 v0, s2
	ds_read_b32 v0, v0
	s_waitcnt lgkmcnt(0)
	v_lshlrev_b32_e32 v0, 6, v0
	v_sub_u32_e32 v0, v148, v0
	v_subrev_u32_e32 v0, 63, v0
	v_cvt_f32_i32_e32 v0, v0
	v_mul_f32_e64 v190, -v146, v0

; DI float shx(float v, int m, int lane) { return __builtin_bit_cast(float, __builtin_amdgcn_ds_bpermute((lane ^ m) << 2, __builtin_bit_cast(int, v))); }
; #define NSA_GATE(k) sigmoidf_(((const float*)(p.ws + WS_SCAL))[(size_t)(b * T + t) * 32 + 8 + hn * 3 + (k)])
; DI float sigmoidf_(float x) { return 1.0f / (1.0f + __expf(-x)); }
; DI void nsa_unit(const P& p, ldsp lds, int u, int l, int wv) {
;     ...
;     { const float lt = c.l + shx(c.l, 32, lane); nsa_store<1>(o, lt > 0.f ? NSA_GATE(1) / lt : 0.f, NSA_OACC, NSA_OROW); }
.LBB0_1056:
	ds_bpermute_b32 v0, v197, v210
	v_mov_b32_e32 v17, 0
	s_waitcnt lgkmcnt(0)
	v_add_f32_e32 v2, v210, v0
	v_cmp_lt_f32_e32 vcc, 0, v2
	v_mov_b32_e32 v0, 0
	s_and_saveexec_b64 s[2:3], vcc
	s_cbranch_execz .LBB0_1058
	v_readlane_b32 s4, v254, 14
	v_readlane_b32 s5, v254, 15
	s_nop 1
	v_lshl_add_u64 v[4:5], v[158:159], 2, s[4:5]
	v_mov_b32_e32 v0, v192
	v_mul_f32_e32 v0, 0xbfb8aa3b, v0
	v_exp_f32_e32 v0, v0
	s_nop 0
	v_add_f32_e32 v0, 1.0, v0
	v_div_scale_f32 v3, s[4:5], v0, v0, 1.0
	v_rcp_f32_e32 v4, v3
	v_div_scale_f32 v5, vcc, 1.0, v0, 1.0
	v_fma_f32 v6, -v3, v4, 1.0
	v_fmac_f32_e32 v4, v6, v4
	v_mul_f32_e32 v6, v5, v4
	v_fma_f32 v7, -v3, v6, v5
	v_fmac_f32_e32 v6, v7, v4
	v_fma_f32 v3, -v3, v6, v5
	v_div_fmas_f32 v3, v3, v4, v6
	v_div_fixup_f32 v0, v3, v0, 1.0
	v_div_scale_f32 v3, s[4:5], v2, v2, v0
	v_rcp_f32_e32 v4, v3
	v_div_scale_f32 v5, vcc, v0, v2, v0
	v_fma_f32 v6, -v3, v4, 1.0
	v_fmac_f32_e32 v4, v6, v4
	v_mul_f32_e32 v6, v5, v4
	v_fma_f32 v7, -v3, v6, v5
	v_fmac_f32_e32 v6, v7, v4
	v_fma_f32 v3, -v3, v6, v5
	v_div_fmas_f32 v3, v3, v4, v6
	v_div_fixup_f32 v0, v3, v2, v0

; DI float shx(float v, int m, int lane) { return __builtin_bit_cast(float, __builtin_amdgcn_ds_bpermute((lane ^ m) << 2, __builtin_bit_cast(int, v))); }
; #define NSA_GATE(k) sigmoidf_(((const float*)(p.ws + WS_SCAL))[(size_t)(b * T + t) * 32 + 8 + hn * 3 + (k)])
; DI float sigmoidf_(float x) { return 1.0f / (1.0f + __expf(-x)); }
; DI void nsa_unit(const P& p, ldsp lds, int u, int l, int wv) {
;     ...
;     { const float lt = c.l + shx(c.l, 32, lane); nsa_store<2>(o, lt > 0.f ? NSA_GATE(2) / lt : 0.f, NSA_OACC, NSA_OROW); }
.LBB0_1076:
	ds_bpermute_b32 v0, v197, v190
	v_mov_b32_e32 v66, 0
	s_waitcnt lgkmcnt(0)
	v_add_f32_e32 v0, v190, v0
	v_cmp_lt_f32_e32 vcc, 0, v0
	s_and_saveexec_b64 s[2:3], vcc
	s_cbranch_execz .LBB0_517
	v_readlane_b32 s0, v254, 16
	v_readlane_b32 s1, v254, 17
	s_nop 1
	v_lshl_add_u64 v[66:67], v[158:159], 2, s[0:1]
	v_mov_b32_e32 v66, v193
	v_mul_f32_e32 v66, 0xbfb8aa3b, v66
	v_exp_f32_e32 v66, v66
	s_nop 0
	v_add_f32_e32 v66, 1.0, v66
	v_div_scale_f32 v67, s[0:1], v66, v66, 1.0
	v_rcp_f32_e32 v68, v67
	v_div_scale_f32 v69, vcc, 1.0, v66, 1.0
	v_fma_f32 v70, -v67, v68, 1.0
	v_fmac_f32_e32 v68, v70, v68
	v_mul_f32_e32 v70, v69, v68
	v_fma_f32 v71, -v67, v70, v69
	v_fmac_f32_e32 v70, v71, v68
	v_fma_f32 v67, -v67, v70, v69
	v_div_fmas_f32 v67, v67, v68, v70
	v_div_fixup_f32 v66, v67, v66, 1.0
	v_div_scale_f32 v67, s[0:1], v0, v0, v66
	v_rcp_f32_e32 v68, v67
	v_div_scale_f32 v69, vcc, v66, v0, v66
	v_fma_f32 v70, -v67, v68, 1.0
	v_fmac_f32_e32 v68, v70, v68
	v_mul_f32_e32 v70, v69, v68
	v_fma_f32 v71, -v67, v70, v69
	v_fmac_f32_e32 v70, v71, v68
	v_fma_f32 v67, -v67, v70, v69
	v_div_fmas_f32 v67, v67, v68, v70
	v_div_fixup_f32 v66, v67, v0, v66
	s_branch .LBB0_517
